# GEMM K-loop: late A-fragment reads issued two per gap after MFMA 1 and 2 (more latency budget before MFMA 9)
# baseline (speedup 1.0000x reference)
; #define LDA(dst, b, h) for (int m = 0; m < 4; ++m) for (int k = 0; k < 2; ++k) \
;     dst[m][k] = *reinterpret_cast<const bf16x8*>(SA(b, h) + lds_byte(wr * 64 + m * 16 + fr, k * 32 + fq * 8))
; #define LDB(dst, b, h) for (int n = 0; n < 2; ++n) for (int k = 0; k < 2; ++k) \
;     dst[n][k] = *reinterpret_cast<const bf16x8*>(SB(b, h) + lds_byte(wc * 32 + n * 16 + fr, k * 32 + fq * 8))
; #define MMA(ai, bj, At_, Bt_) do { __builtin_amdgcn_s_setprio(1); \
;     for (int m = 0; m < 4; ++m) for (int n = 0; n < 2; ++n) for (int k = 0; k < 2; ++k) \
;       acc[ai][bj][m][n] = __builtin_amdgcn_mfma_f32_16x16x32_bf16(Bt_[n][k], At_[m][k], acc[ai][bj][m][n], 0, 0, 0); \
;     __builtin_amdgcn_s_setprio(0); } while (0)
; #define WAIT_L(n) asm volatile("s_waitcnt lgkmcnt(" #n ")" ::: "memory")
; #define BAR __builtin_amdgcn_s_barrier()
; #define SCHED __builtin_amdgcn_sched_barrier(0)
; #define STG(P, PTR, LD, O0) do { const bf16_t* _g = (PTR); \
;     __builtin_amdgcn_global_load_lds((const unsigned*)(_g + O0), (lds_u32*)((P) + swave * 1024), 16, 0, 0); \
;     __builtin_amdgcn_global_load_lds((const unsigned*)(_g + (size_t)64 * (LD) + O0), (lds_u32*)((P) + swave * 1024 + 8192), 16, 0, 0); } while (0)
; #define LDA(dst, b, h) for (int m = 0; m < 4; ++m) for (int k = 0; k < 2; ++k) \
;     dst[m][k] = *reinterpret_cast<const bf16x8*>(SA(b, h) + lds_byte(wr * 64 + m * 16 + fr, k * 32 + fq * 8))
; #define LDB(dst, b, h) for (int n = 0; n < 2; ++n) for (int k = 0; k < 2; ++k) \
;     dst[n][k] = *reinterpret_cast<const bf16x8*>(SB(b, h) + lds_byte(wc * 32 + n * 16 + fr, k * 32 + fq * 8))
; __device__ __forceinline__ void gemm_stream(int swave, const GemmJob& J, char* shm, int vb, int G) {
;     ...
;       const bool last = (t == nt - 2);
;       const bf16_t* xA = last ? nA : cA; const bf16_t* xA1 = last ? nA1 : cA1; const int k2 = last ? 0 : t + 2;
;       const bf16_t* b2 = last ? nB : cB + (size_t)(t + 2) * 64; const bf16_t* b3 = b2 + 64;
;       LDB(B0, 0, 0); SCHED; LDA(At, 0, 0); STGA(SA(1, 1), cA, cA1, t + 1, 1);
;       WAIT_L(8); BAR; WAIT_L(0); MMA(0, 0, At, B0); BAR; SCHED;
;       LDB(B1, 0, 1); STG(SB(0, 0), b2, ldb, offB0);
;       BAR; WAIT_L(0); MMA(0, 1, At, B1); BAR;
;       LDA(At, 0, 1); STGA(SA(0, 0), xA, xA1, k2, 0);
;       BAR; WAIT_L(0); MMA(1, 0, At, B0); BAR; SCHED;
;       STG(SB(0, 1), b2 + hB, ldb, offB0);
.LBB0_729:
	ds_read_b128 v[164:167], v139
	ds_read_b128 v[168:171], v139 offset:1024
	ds_read_b128 v[172:175], v139 offset:2048
	ds_read_b128 v[176:179], v139 offset:3072
	s_cmp_eq_u32 s49, s29
	s_cselect_b64 s[68:69], -1, 0
	s_and_b64 s[64:65], s[68:69], exec
	s_cselect_b32 s52, s10, s8
	s_cselect_b32 s64, s11, s9
	s_add_i32 s33, s2, 2
	s_and_b64 s[68:69], s[68:69], exec
	s_cselect_b32 s71, s15, s21
	s_cselect_b32 s70, s14, s20
	s_cselect_b32 s68, 0, s33
	s_cselect_b32 s65, s12, s16
	s_cselect_b32 s66, s13, s17
	s_or_b32 s2, s2, 1
	s_cmp_lt_u32 s2, s36
	s_cselect_b64 vcc, -1, 0
	s_and_b64 s[2:3], vcc, exec
	s_cselect_b32 s3, 0, s36
	s_cselect_b32 s2, s38, s37
	s_not_b32 s3, s3
	s_add_i32 s94, s3, s29
	s_and_b64 s[72:73], vcc, exec
	s_cselect_b32 s3, s9, s17
	s_cselect_b32 s69, s8, s16
	s_lshl_b64 s[72:73], s[94:95], 7
	s_add_u32 s69, s69, s72
	s_addc_u32 s74, s3, s73
	s_mov_b32 s3, s95
	s_lshl_b64 s[72:73], s[2:3], 8
	s_add_u32 s72, s69, s72
	v_cndmask_b32_e32 v2, v138, v0, vcc
	s_addc_u32 s73, s74, s73
	s_add_i32 m0, s42, 0xc000
	s_lshl_b64 s[2:3], s[2:3], 7
	v_lshlrev_b64 v[212:213], 1, v[2:3]
	s_add_u32 s2, s72, s2
	v_lshl_add_u64 v[214:215], s[72:73], 0, v[212:213]
	s_addc_u32 s3, s73, s3
	ds_read_b128 v[180:183], v144
	ds_read_b128 v[188:191], v145
	ds_read_b128 v[196:199], v159
	ds_read_b128 v[204:207], v160
	global_load_lds_dwordx4 v[214:215], off
	v_lshl_add_u64 v[212:213], s[2:3], 0, v[212:213]
	s_add_i32 m0, s42, 0xe000
	s_nop 0
	global_load_lds_dwordx4 v[212:213], off
	s_waitcnt lgkmcnt(4)
	s_barrier
	s_waitcnt lgkmcnt(0)
	v_mfma_f32_16x16x32_bf16 v[128:131], v[164:167], v[180:183], v[128:131]
	ds_read_b128 v[184:187], v144 offset:1024
	ds_read_b128 v[192:195], v145 offset:1024
	v_mfma_f32_16x16x32_bf16 v[124:127], v[172:175], v[180:183], v[124:127]
	ds_read_b128 v[200:203], v159 offset:1024
	ds_read_b128 v[208:211], v160 offset:1024
	v_mfma_f32_16x16x32_bf16 v[120:123], v[164:167], v[188:191], v[120:123]
	v_mfma_f32_16x16x32_bf16 v[116:119], v[172:175], v[188:191], v[116:119]
	v_mfma_f32_16x16x32_bf16 v[104:107], v[164:167], v[196:199], v[104:107]
	v_mfma_f32_16x16x32_bf16 v[100:103], v[172:175], v[196:199], v[100:103]
	v_mfma_f32_16x16x32_bf16 v[88:91], v[164:167], v[204:207], v[88:91]
	v_mfma_f32_16x16x32_bf16 v[84:87], v[172:175], v[204:207], v[84:87]
	s_waitcnt lgkmcnt(0)
	v_mfma_f32_16x16x32_bf16 v[128:131], v[168:171], v[184:187], v[128:131]
	v_mfma_f32_16x16x32_bf16 v[124:127], v[176:179], v[184:187], v[124:127]
	v_mfma_f32_16x16x32_bf16 v[120:123], v[168:171], v[192:195], v[120:123]
	v_mfma_f32_16x16x32_bf16 v[116:119], v[176:179], v[192:195], v[116:119]
	v_mfma_f32_16x16x32_bf16 v[104:107], v[168:171], v[200:203], v[104:107]
	v_mfma_f32_16x16x32_bf16 v[100:103], v[176:179], v[200:203], v[100:103]
	v_mfma_f32_16x16x32_bf16 v[88:91], v[168:171], v[208:211], v[88:91]
	v_mfma_f32_16x16x32_bf16 v[84:87], v[176:179], v[208:211], v[84:87]
	s_barrier
	s_add_u32 s2, s70, s0
	s_mov_b32 m0, s43
	v_lshl_add_u64 v[228:229], s[70:71], 0, v[136:137]
	s_addc_u32 s3, s71, s1
	ds_read_b128 v[212:215], v161
	ds_read_b128 v[216:219], v161 offset:1024
	ds_read_b128 v[220:223], v161 offset:2048
	ds_read_b128 v[224:227], v161 offset:3072
	global_load_lds_dwordx4 v[228:229], off
	v_lshl_add_u64 v[230:231], s[2:3], 0, v[136:137]
	s_mov_b32 m0, s44
	s_nop 0
	global_load_lds_dwordx4 v[230:231], off
	s_barrier
	s_waitcnt lgkmcnt(0)
	v_mfma_f32_16x16x32_bf16 v[112:115], v[212:215], v[180:183], v[112:115]
	v_mfma_f32_16x16x32_bf16 v[108:111], v[220:223], v[180:183], v[108:111]
	s_cmp_lt_u32 s68, s36
	s_cselect_b64 vcc, -1, 0
	v_mfma_f32_16x16x32_bf16 v[96:99], v[212:215], v[188:191], v[96:99]
	s_and_b64 s[70:71], vcc, exec
	s_cselect_b32 s70, s38, s37
	v_mfma_f32_16x16x32_bf16 v[92:95], v[220:223], v[188:191], v[92:95]
	s_sub_i32 s69, s68, s36
	s_min_u32 s94, s68, s69
	v_mfma_f32_16x16x32_bf16 v[80:83], v[212:215], v[196:199], v[80:83]
	s_and_b64 s[72:73], vcc, exec
	s_cselect_b32 s69, s64, s66
	v_mfma_f32_16x16x32_bf16 v[76:79], v[220:223], v[196:199], v[76:79]
	s_cselect_b32 s71, s52, s65
	s_lshl_b64 s[72:73], s[94:95], 7
	v_mfma_f32_16x16x32_bf16 v[72:75], v[212:215], v[204:207], v[72:75]
	v_cndmask_b32_e32 v2, v138, v0, vcc
	s_add_u32 s72, s71, s72
	v_mfma_f32_16x16x32_bf16 v[68:71], v[220:223], v[204:207], v[68:71]
	s_mov_b32 s71, s95
	v_mfma_f32_16x16x32_bf16 v[112:115], v[216:219], v[184:187], v[112:115]
	s_addc_u32 s73, s69, s73
	v_mfma_f32_16x16x32_bf16 v[108:111], v[224:227], v[184:187], v[108:111]
	v_lshlrev_b64 v[232:233], 1, v[2:3]
	v_mfma_f32_16x16x32_bf16 v[96:99], v[216:219], v[192:195], v[96:99]
	s_lshl_b64 s[70:71], s[70:71], 7
	v_mfma_f32_16x16x32_bf16 v[92:95], v[224:227], v[192:195], v[92:95]
	v_lshl_add_u64 v[234:235], s[72:73], 0, v[232:233]
	v_mfma_f32_16x16x32_bf16 v[80:83], v[216:219], v[200:203], v[80:83]
	s_add_u32 s72, s72, s70
	v_mfma_f32_16x16x32_bf16 v[76:79], v[224:227], v[200:203], v[76:79]
	s_mov_b32 m0, s42
	v_mfma_f32_16x16x32_bf16 v[72:75], v[216:219], v[208:211], v[72:75]
	s_addc_u32 s73, s73, s71
	v_mfma_f32_16x16x32_bf16 v[68:71], v[224:227], v[208:211], v[68:71]
	s_barrier
	ds_read_b128 v[180:183], v144 offset:16384
	ds_read_b128 v[188:191], v145 offset:16384
	ds_read_b128 v[196:199], v159 offset:16384
	ds_read_b128 v[204:207], v160 offset:16384
	global_load_lds_dwordx4 v[234:235], off
	v_lshl_add_u64 v[234:235], s[72:73], 0, v[232:233]
	s_mov_b32 m0, s39
	s_nop 0
	global_load_lds_dwordx4 v[234:235], off
	s_barrier
; #define LDA(dst, b, h) for (int m = 0; m < 4; ++m) for (int k = 0; k < 2; ++k) \
;     dst[m][k] = *reinterpret_cast<const bf16x8*>(SA(b, h) + lds_byte(wr * 64 + m * 16 + fr, k * 32 + fq * 8))
; #define LDB(dst, b, h) for (int n = 0; n < 2; ++n) for (int k = 0; k < 2; ++k) \
;     dst[n][k] = *reinterpret_cast<const bf16x8*>(SB(b, h) + lds_byte(wc * 32 + n * 16 + fr, k * 32 + fq * 8))
; #define MMA(ai, bj, At_, Bt_) do { __builtin_amdgcn_s_setprio(1); \
;     for (int m = 0; m < 4; ++m) for (int n = 0; n < 2; ++n) for (int k = 0; k < 2; ++k) \
;       acc[ai][bj][m][n] = __builtin_amdgcn_mfma_f32_16x16x32_bf16(Bt_[n][k], At_[m][k], acc[ai][bj][m][n], 0, 0, 0); \
;     __builtin_amdgcn_s_setprio(0); } while (0)
; #define WAIT_V(n) asm volatile("s_waitcnt vmcnt(" #n ")" ::: "memory")
; #define WAIT_L(n) asm volatile("s_waitcnt lgkmcnt(" #n ")" ::: "memory")
; #define BAR __builtin_amdgcn_s_barrier()
; #define SCHED __builtin_amdgcn_sched_barrier(0)
; #define STG(P, PTR, LD, O0) do { const bf16_t* _g = (PTR); \
;     __builtin_amdgcn_global_load_lds((const unsigned*)(_g + O0), (lds_u32*)((P) + swave * 1024), 16, 0, 0); \
;     __builtin_amdgcn_global_load_lds((const unsigned*)(_g + (size_t)64 * (LD) + O0), (lds_u32*)((P) + swave * 1024 + 8192), 16, 0, 0); } while (0)
; #define LDA(dst, b, h) for (int m = 0; m < 4; ++m) for (int k = 0; k < 2; ++k) \
;     dst[m][k] = *reinterpret_cast<const bf16x8*>(SA(b, h) + lds_byte(wr * 64 + m * 16 + fr, k * 32 + fq * 8))
; #define LDB(dst, b, h) for (int n = 0; n < 2; ++n) for (int k = 0; k < 2; ++k) \
;     dst[n][k] = *reinterpret_cast<const bf16x8*>(SB(b, h) + lds_byte(wc * 32 + n * 16 + fr, k * 32 + fq * 8))
; #define WAIT_V(n) asm volatile("s_waitcnt vmcnt(" #n ")" ::: "memory")
; #define WAIT_L(n) asm volatile("s_waitcnt lgkmcnt(" #n ")" ::: "memory")
; #define BAR __builtin_amdgcn_s_barrier()
; #define SCHED __builtin_amdgcn_sched_barrier(0)
; __device__ __forceinline__ void gemm_stream(int swave, const GemmJob& J, char* shm, int vb, int G) {
;     ...
;       BAR; WAIT_L(0); MMA(1, 0, At, B0); BAR; SCHED;
;       STG(SB(0, 1), b2 + hB, ldb, offB0);
;       WAIT_V(6); BAR; MMA(1, 1, At, B1); BAR;
;       LDB(B0, 1, 0); SCHED; LDA(At, 1, 0); STGA(SA(0, 1), xA, xA1, k2, 1);
;       WAIT_L(8); BAR; WAIT_L(0); MMA(0, 0, At, B0); BAR; SCHED;
;       LDB(B1, 1, 1); STG(SB(1, 0), b3, ldb, offB0);
	s_waitcnt lgkmcnt(0)
	v_mfma_f32_16x16x32_bf16 v[64:67], v[164:167], v[180:183], v[64:67]
	ds_read_b128 v[184:187], v144 offset:17408
	ds_read_b128 v[192:195], v145 offset:17408
	v_mfma_f32_16x16x32_bf16 v[60:63], v[172:175], v[180:183], v[60:63]
	ds_read_b128 v[200:203], v159 offset:17408
	ds_read_b128 v[208:211], v160 offset:17408
	v_mfma_f32_16x16x32_bf16 v[56:59], v[164:167], v[188:191], v[56:59]
	v_mfma_f32_16x16x32_bf16 v[52:55], v[172:175], v[188:191], v[52:55]
	v_mfma_f32_16x16x32_bf16 v[40:43], v[164:167], v[196:199], v[40:43]
	v_mfma_f32_16x16x32_bf16 v[36:39], v[172:175], v[196:199], v[36:39]
	v_mfma_f32_16x16x32_bf16 v[24:27], v[164:167], v[204:207], v[24:27]
	v_mfma_f32_16x16x32_bf16 v[20:23], v[172:175], v[204:207], v[20:23]
	s_waitcnt lgkmcnt(0)
	v_mfma_f32_16x16x32_bf16 v[64:67], v[168:171], v[184:187], v[64:67]
	v_mfma_f32_16x16x32_bf16 v[60:63], v[176:179], v[184:187], v[60:63]
	v_mfma_f32_16x16x32_bf16 v[56:59], v[168:171], v[192:195], v[56:59]
	v_mfma_f32_16x16x32_bf16 v[52:55], v[176:179], v[192:195], v[52:55]
	v_mfma_f32_16x16x32_bf16 v[40:43], v[168:171], v[200:203], v[40:43]
	v_mfma_f32_16x16x32_bf16 v[36:39], v[176:179], v[200:203], v[36:39]
	v_mfma_f32_16x16x32_bf16 v[24:27], v[168:171], v[208:211], v[24:27]
	v_mfma_f32_16x16x32_bf16 v[20:23], v[176:179], v[208:211], v[20:23]
	s_barrier
	s_add_u32 s2, s2, s0
	s_addc_u32 s3, s3, s1
	v_lshl_add_u64 v[234:235], s[2:3], 0, v[136:137]
	s_add_u32 s2, s2, s0
	s_mov_b32 m0, s45
	s_addc_u32 s3, s3, s1
	global_load_lds_dwordx4 v[234:235], off
	v_lshl_add_u64 v[236:237], s[2:3], 0, v[136:137]
	s_mov_b32 m0, s46
	s_nop 0
	global_load_lds_dwordx4 v[236:237], off
	s_waitcnt vmcnt(6)
	s_barrier
	v_mfma_f32_16x16x32_bf16 v[48:51], v[212:215], v[180:183], v[48:51]
	v_mfma_f32_16x16x32_bf16 v[44:47], v[220:223], v[180:183], v[44:47]
	v_mfma_f32_16x16x32_bf16 v[32:35], v[212:215], v[188:191], v[32:35]
	v_mfma_f32_16x16x32_bf16 v[28:31], v[220:223], v[188:191], v[28:31]
	v_mfma_f32_16x16x32_bf16 v[16:19], v[212:215], v[196:199], v[16:19]
	v_mfma_f32_16x16x32_bf16 v[12:15], v[220:223], v[196:199], v[12:15]
	v_mfma_f32_16x16x32_bf16 v[8:11], v[212:215], v[204:207], v[8:11]
	v_mfma_f32_16x16x32_bf16 v[4:7], v[220:223], v[204:207], v[4:7]
	v_mfma_f32_16x16x32_bf16 v[48:51], v[216:219], v[184:187], v[48:51]
	v_mfma_f32_16x16x32_bf16 v[44:47], v[224:227], v[184:187], v[44:47]
	v_mfma_f32_16x16x32_bf16 v[32:35], v[216:219], v[192:195], v[32:35]
	v_mfma_f32_16x16x32_bf16 v[28:31], v[224:227], v[192:195], v[28:31]
	v_mfma_f32_16x16x32_bf16 v[16:19], v[216:219], v[200:203], v[16:19]
	v_mfma_f32_16x16x32_bf16 v[12:15], v[224:227], v[200:203], v[12:15]
	v_mfma_f32_16x16x32_bf16 v[8:11], v[216:219], v[208:211], v[8:11]
	v_mfma_f32_16x16x32_bf16 v[4:7], v[224:227], v[208:211], v[4:7]
	s_barrier
	ds_read_b128 v[164:167], v162
	ds_read_b128 v[168:171], v162 offset:1024
	ds_read_b128 v[172:175], v162 offset:2048
	ds_read_b128 v[176:179], v162 offset:3072
	s_add_u32 s2, s72, s70
	s_addc_u32 s3, s73, s71
	v_lshl_add_u64 v[212:213], s[2:3], 0, v[232:233]
	s_add_u32 s2, s2, s70
	s_mov_b32 m0, s47
	s_addc_u32 s3, s3, s71
	ds_read_b128 v[180:183], v144 offset:32768
	ds_read_b128 v[188:191], v145 offset:32768
	ds_read_b128 v[196:199], v159 offset:32768
	ds_read_b128 v[204:207], v160 offset:32768
	global_load_lds_dwordx4 v[212:213], off
	v_lshl_add_u64 v[212:213], s[2:3], 0, v[232:233]
	s_mov_b32 m0, s48
	s_nop 0
	global_load_lds_dwordx4 v[212:213], off
	s_waitcnt lgkmcnt(4)
	s_barrier
	s_waitcnt lgkmcnt(0)
	v_mfma_f32_16x16x32_bf16 v[128:131], v[164:167], v[180:183], v[128:131]
	ds_read_b128 v[184:187], v144 offset:33792
	ds_read_b128 v[192:195], v145 offset:33792
	v_mfma_f32_16x16x32_bf16 v[124:127], v[172:175], v[180:183], v[124:127]
	ds_read_b128 v[200:203], v159 offset:33792
	ds_read_b128 v[208:211], v160 offset:33792
	v_mfma_f32_16x16x32_bf16 v[120:123], v[164:167], v[188:191], v[120:123]
	v_mfma_f32_16x16x32_bf16 v[116:119], v[172:175], v[188:191], v[116:119]
	v_mfma_f32_16x16x32_bf16 v[104:107], v[164:167], v[196:199], v[104:107]
	v_mfma_f32_16x16x32_bf16 v[100:103], v[172:175], v[196:199], v[100:103]
	v_mfma_f32_16x16x32_bf16 v[88:91], v[164:167], v[204:207], v[88:91]
	v_mfma_f32_16x16x32_bf16 v[84:87], v[172:175], v[204:207], v[84:87]
	s_waitcnt lgkmcnt(0)
	v_mfma_f32_16x16x32_bf16 v[128:131], v[168:171], v[184:187], v[128:131]
	v_mfma_f32_16x16x32_bf16 v[124:127], v[176:179], v[184:187], v[124:127]
	v_mfma_f32_16x16x32_bf16 v[120:123], v[168:171], v[192:195], v[120:123]
	v_mfma_f32_16x16x32_bf16 v[116:119], v[176:179], v[192:195], v[116:119]
	v_mfma_f32_16x16x32_bf16 v[104:107], v[168:171], v[200:203], v[104:107]
	v_mfma_f32_16x16x32_bf16 v[100:103], v[176:179], v[200:203], v[100:103]
	v_mfma_f32_16x16x32_bf16 v[88:91], v[168:171], v[208:211], v[88:91]
	v_mfma_f32_16x16x32_bf16 v[84:87], v[176:179], v[208:211], v[84:87]
	s_barrier
	v_lshl_add_u64 v[228:229], v[228:229], 0, s[22:23]
	s_add_i32 m0, s42, 0x18000
	ds_read_b128 v[212:215], v163
	ds_read_b128 v[216:219], v163 offset:1024
	ds_read_b128 v[220:223], v163 offset:2048
	ds_read_b128 v[224:227], v163 offset:3072
	global_load_lds_dwordx4 v[228:229], off
	v_lshl_add_u64 v[228:229], v[230:231], 0, s[22:23]
	s_add_i32 m0, s42, 0x1a000
	s_nop 0
	global_load_lds_dwordx4 v[228:229], off
	s_barrier
; #define LDA(dst, b, h) for (int m = 0; m < 4; ++m) for (int k = 0; k < 2; ++k) \
;     dst[m][k] = *reinterpret_cast<const bf16x8*>(SA(b, h) + lds_byte(wr * 64 + m * 16 + fr, k * 32 + fq * 8))
; #define MMA(ai, bj, At_, Bt_) do { __builtin_amdgcn_s_setprio(1); \
;     for (int m = 0; m < 4; ++m) for (int n = 0; n < 2; ++n) for (int k = 0; k < 2; ++k) \
;       acc[ai][bj][m][n] = __builtin_amdgcn_mfma_f32_16x16x32_bf16(Bt_[n][k], At_[m][k], acc[ai][bj][m][n], 0, 0, 0); \
;     __builtin_amdgcn_s_setprio(0); } while (0)
; #define WAIT_V(n) asm volatile("s_waitcnt vmcnt(" #n ")" ::: "memory")
; #define WAIT_L(n) asm volatile("s_waitcnt lgkmcnt(" #n ")" ::: "memory")
; #define BAR __builtin_amdgcn_s_barrier()
; #define SCHED __builtin_amdgcn_sched_barrier(0)
; #define STG(P, PTR, LD, O0) do { const bf16_t* _g = (PTR); \
;     __builtin_amdgcn_global_load_lds((const unsigned*)(_g + O0), (lds_u32*)((P) + swave * 1024), 16, 0, 0); \
;     __builtin_amdgcn_global_load_lds((const unsigned*)(_g + (size_t)64 * (LD) + O0), (lds_u32*)((P) + swave * 1024 + 8192), 16, 0, 0); } while (0)
; #define LDA(dst, b, h) for (int m = 0; m < 4; ++m) for (int k = 0; k < 2; ++k) \
;     dst[m][k] = *reinterpret_cast<const bf16x8*>(SA(b, h) + lds_byte(wr * 64 + m * 16 + fr, k * 32 + fq * 8))
; #define MMA(ai, bj, At_, Bt_) do { __builtin_amdgcn_s_setprio(1); \
;     for (int m = 0; m < 4; ++m) for (int n = 0; n < 2; ++n) for (int k = 0; k < 2; ++k) \
;       acc[ai][bj][m][n] = __builtin_amdgcn_mfma_f32_16x16x32_bf16(Bt_[n][k], At_[m][k], acc[ai][bj][m][n], 0, 0, 0); \
;     __builtin_amdgcn_s_setprio(0); } while (0)
; #define WAIT_V(n) asm volatile("s_waitcnt vmcnt(" #n ")" ::: "memory")
; #define WAIT_L(n) asm volatile("s_waitcnt lgkmcnt(" #n ")" ::: "memory")
; #define BAR __builtin_amdgcn_s_barrier()
; #define SCHED __builtin_amdgcn_sched_barrier(0)
; __device__ __forceinline__ void gemm_stream(int swave, const GemmJob& J, char* shm, int vb, int G) {
;     ...
;       BAR; WAIT_L(0); MMA(0, 1, At, B1); BAR;
;       LDA(At, 1, 1); STGA(SA(1, 0), xA, xA1, k2 + 1, 0);
;       BAR; WAIT_L(0); MMA(1, 0, At, B0); BAR; SCHED;
;       STG(SB(1, 1), b3 + hB, ldb, offB0);
;       WAIT_V(6); BAR; MMA(1, 1, At, B1); BAR;
	s_waitcnt lgkmcnt(0)
	v_mfma_f32_16x16x32_bf16 v[112:115], v[212:215], v[180:183], v[112:115]
	v_mfma_f32_16x16x32_bf16 v[108:111], v[220:223], v[180:183], v[108:111]
	s_or_b32 s68, s68, 1
	s_cmp_lt_u32 s68, s36
	v_mfma_f32_16x16x32_bf16 v[96:99], v[212:215], v[188:191], v[96:99]
	s_cselect_b64 vcc, -1, 0
	s_and_b64 s[2:3], vcc, exec
	v_mfma_f32_16x16x32_bf16 v[92:95], v[220:223], v[188:191], v[92:95]
	s_cselect_b32 s69, s38, s37
	s_sub_i32 s2, s68, s36
	v_mfma_f32_16x16x32_bf16 v[80:83], v[212:215], v[196:199], v[80:83]
	s_min_u32 s94, s68, s2
	s_and_b64 s[2:3], vcc, exec
	v_mfma_f32_16x16x32_bf16 v[76:79], v[220:223], v[196:199], v[76:79]
	s_cselect_b32 s64, s64, s66
	s_cselect_b32 s52, s52, s65
	v_mfma_f32_16x16x32_bf16 v[72:75], v[212:215], v[204:207], v[72:75]
	s_lshl_b64 s[2:3], s[94:95], 7
	v_cndmask_b32_e32 v2, v138, v0, vcc
	v_mfma_f32_16x16x32_bf16 v[68:71], v[220:223], v[204:207], v[68:71]
	s_add_u32 s2, s52, s2
	v_mfma_f32_16x16x32_bf16 v[112:115], v[216:219], v[184:187], v[112:115]
	s_addc_u32 s3, s64, s3
	v_mfma_f32_16x16x32_bf16 v[108:111], v[224:227], v[184:187], v[108:111]
	v_lshlrev_b64 v[228:229], 1, v[2:3]
	v_mfma_f32_16x16x32_bf16 v[96:99], v[216:219], v[192:195], v[96:99]
	s_lshl_b32 s52, s69, 7
	v_mfma_f32_16x16x32_bf16 v[92:95], v[224:227], v[192:195], v[92:95]
	v_lshl_add_u64 v[230:231], s[2:3], 0, v[228:229]
	v_mfma_f32_16x16x32_bf16 v[80:83], v[216:219], v[200:203], v[80:83]
	s_add_u32 s2, s2, s52
	v_mfma_f32_16x16x32_bf16 v[76:79], v[224:227], v[200:203], v[76:79]
	s_mov_b32 m0, s54
	v_mfma_f32_16x16x32_bf16 v[72:75], v[216:219], v[208:211], v[72:75]
	s_addc_u32 s3, s3, 0
	v_mfma_f32_16x16x32_bf16 v[68:71], v[224:227], v[208:211], v[68:71]
	s_barrier
	ds_read_b128 v[180:183], v144 offset:49152
	ds_read_b128 v[188:191], v145 offset:49152
	ds_read_b128 v[196:199], v159 offset:49152
	ds_read_b128 v[204:207], v160 offset:49152
	global_load_lds_dwordx4 v[230:231], off
	v_lshl_add_u64 v[228:229], s[2:3], 0, v[228:229]
	s_mov_b32 m0, s55
	s_nop 0
	global_load_lds_dwordx4 v[228:229], off
	s_barrier
	s_waitcnt lgkmcnt(0)
	v_mfma_f32_16x16x32_bf16 v[64:67], v[164:167], v[180:183], v[64:67]
	ds_read_b128 v[184:187], v144 offset:50176
	ds_read_b128 v[192:195], v145 offset:50176
	v_mfma_f32_16x16x32_bf16 v[60:63], v[172:175], v[180:183], v[60:63]
	ds_read_b128 v[200:203], v159 offset:50176
	ds_read_b128 v[208:211], v160 offset:50176
	v_mfma_f32_16x16x32_bf16 v[56:59], v[164:167], v[188:191], v[56:59]
	v_mfma_f32_16x16x32_bf16 v[52:55], v[172:175], v[188:191], v[52:55]
	v_mfma_f32_16x16x32_bf16 v[40:43], v[164:167], v[196:199], v[40:43]
	v_mfma_f32_16x16x32_bf16 v[36:39], v[172:175], v[196:199], v[36:39]
	v_mfma_f32_16x16x32_bf16 v[24:27], v[164:167], v[204:207], v[24:27]
	v_mfma_f32_16x16x32_bf16 v[20:23], v[172:175], v[204:207], v[20:23]
	s_waitcnt lgkmcnt(0)
	v_mfma_f32_16x16x32_bf16 v[64:67], v[168:171], v[184:187], v[64:67]
	v_mfma_f32_16x16x32_bf16 v[60:63], v[176:179], v[184:187], v[60:63]
	v_mfma_f32_16x16x32_bf16 v[56:59], v[168:171], v[192:195], v[56:59]
	v_mfma_f32_16x16x32_bf16 v[52:55], v[176:179], v[192:195], v[52:55]
	v_mfma_f32_16x16x32_bf16 v[40:43], v[168:171], v[200:203], v[40:43]
	v_mfma_f32_16x16x32_bf16 v[36:39], v[176:179], v[200:203], v[36:39]
	v_mfma_f32_16x16x32_bf16 v[24:27], v[168:171], v[208:211], v[24:27]
	v_mfma_f32_16x16x32_bf16 v[20:23], v[176:179], v[208:211], v[20:23]
	s_barrier
	v_lshl_add_u64 v[164:165], v[234:235], 0, s[22:23]
	s_add_i32 m0, s42, 0x1c000
	s_nop 0
	global_load_lds_dwordx4 v[164:165], off
	v_lshl_add_u64 v[164:165], v[236:237], 0, s[22:23]
	s_add_i32 m0, s42, 0x1e000
	s_nop 0
	global_load_lds_dwordx4 v[164:165], off
	s_waitcnt vmcnt(6)
	s_barrier
	v_mfma_f32_16x16x32_bf16 v[48:51], v[212:215], v[180:183], v[48:51]
	v_mfma_f32_16x16x32_bf16 v[44:47], v[220:223], v[180:183], v[44:47]
	s_add_i32 s29, s29, 2
	v_mfma_f32_16x16x32_bf16 v[32:35], v[212:215], v[188:191], v[32:35]
	s_add_u32 s20, s20, 0x100
	v_mfma_f32_16x16x32_bf16 v[28:31], v[220:223], v[188:191], v[28:31]
	s_addc_u32 s21, s21, 0
	v_mfma_f32_16x16x32_bf16 v[16:19], v[212:215], v[196:199], v[16:19]
	s_cmp_ge_u32 s33, s49
	v_mfma_f32_16x16x32_bf16 v[12:15], v[220:223], v[196:199], v[12:15]
	s_mov_b32 s2, s33
	v_mfma_f32_16x16x32_bf16 v[8:11], v[212:215], v[204:207], v[8:11]
	v_mfma_f32_16x16x32_bf16 v[4:7], v[220:223], v[204:207], v[4:7]
	v_mfma_f32_16x16x32_bf16 v[48:51], v[216:219], v[184:187], v[48:51]
	v_mfma_f32_16x16x32_bf16 v[44:47], v[224:227], v[184:187], v[44:47]
	v_mfma_f32_16x16x32_bf16 v[32:35], v[216:219], v[192:195], v[32:35]
	v_mfma_f32_16x16x32_bf16 v[28:31], v[224:227], v[192:195], v[28:31]
	v_mfma_f32_16x16x32_bf16 v[16:19], v[216:219], v[200:203], v[16:19]
	v_mfma_f32_16x16x32_bf16 v[12:15], v[224:227], v[200:203], v[12:15]
	v_mfma_f32_16x16x32_bf16 v[8:11], v[216:219], v[208:211], v[8:11]
	v_mfma_f32_16x16x32_bf16 v[4:7], v[224:227], v[208:211], v[4:7]
	s_barrier
; __device__ __forceinline__ unsigned pk2(float lo, float hi) { f32x2_t v = {lo, hi}; bf16x2_t b = __builtin_convertvector(v, bf16x2_t); return __builtin_bit_cast(unsigned, b); }
; #define WAIT_V(n) asm volatile("s_waitcnt vmcnt(" #n ")" ::: "memory")
; #define BAR __builtin_amdgcn_s_barrier()
; #define WAIT_V(n) asm volatile("s_waitcnt vmcnt(" #n ")" ::: "memory")
; #define BAR __builtin_amdgcn_s_barrier()
; __device__ __forceinline__ void gemm_stream(int swave, const GemmJob& J, char* shm, int vb, int G) {
;     ...
;     {
;       bf16_t* C = (bf16_t*)((char*)J.c0 + (size_t)cg * J.strideC);
; #pragma unroll
;       for (int ai = 0; ai < 2; ++ai)
; #pragma unroll
;         for (int m = 0; m < 4; ++m)
; #pragma unroll
;           for (int bj = 0; bj < 2; ++bj) {
;             const f32x4 v0 = acc[ai][bj][m][0], v1 = acc[ai][bj][m][1];
;             uint4 o; o.x = pk2(v0[0], v0[1]); o.y = pk2(v0[2], v0[3]); o.z = pk2(v1[0], v1[1]); o.w = pk2(v1[2], v1[3]);
;             *(uint4*)(C + (size_t)(cbrow + ai * 128 + wr * 64 + m * 16 + fr) * J.ldc + cbcol + bj * 128 + wc * 32 + fq * 8) = o;
;           }
;     }
;     if (!has_next) break;
; #pragma unroll
;     for (int a_ = 0; a_ < 2; ++a_)
; #pragma unroll
;       for (int b_ = 0; b_ < 2; ++b_)
; #pragma unroll
;         for (int m = 0; m < 4; ++m)
; #pragma unroll
;           for (int n = 0; n < 2; ++n) acc[a_][b_][m][n] = (f32x4){0.f, 0.f, 0.f, 0.f};
;     id = nid; cg = ng; cbrow = nbrow; cbcol = nbcol; cA = nA; cA1 = nA1; cB = nB;
;   }
;   WAIT_V(0);
;   if (wr == 0) BAR;
	s_cbranch_scc0 .LBB0_729
	v_add_u32_e32 v164, s5, v1
	s_ashr_i32 s5, s4, 31
	s_lshl_b64 s[2:3], s[4:5], 1
	v_ashrrev_i32_e32 v2, 31, v164
	s_add_u32 s2, s50, s2
	v_cvt_pk_bf16_f32 v128, v128, v129
	v_cvt_pk_bf16_f32 v129, v130, v131
	v_cvt_pk_bf16_f32 v130, v124, v125
	v_mul_lo_u32 v2, v2, s18
	v_mad_u64_u32 v[124:125], s[4:5], v164, s18, 0
	s_addc_u32 s3, s51, s3
	v_add_u32_e32 v125, v125, v2
	v_lshl_add_u64 v[124:125], v[124:125], 1, s[2:3]
	v_mov_b32_e32 v141, v3
	v_lshl_add_u64 v[124:125], v[124:125], 0, v[140:141]
	v_mov_b32_e32 v143, v3
	v_lshl_add_u64 v[124:125], v[124:125], 0, v[142:143]
	s_lshl_b32 s2, s18, 5
	s_mov_b32 s3, 0
	s_mul_i32 s4, s18, 0xa0
	s_mov_b32 s5, 0
	v_cvt_pk_bf16_f32 v112, v112, v113
	v_cvt_pk_bf16_f32 v113, v114, v115
	v_cvt_pk_bf16_f32 v114, v108, v109
	v_cvt_pk_bf16_f32 v115, v110, v111
	global_store_dwordx4 v[124:125], v[112:115], off offset:256
	v_cvt_pk_bf16_f32 v131, v126, v127
	v_cvt_pk_bf16_f32 v96, v96, v97
	v_lshl_add_u64 v[112:113], v[124:125], 0, s[2:3]
	v_cvt_pk_bf16_f32 v97, v98, v99
	v_cvt_pk_bf16_f32 v98, v92, v93
	v_cvt_pk_bf16_f32 v99, v94, v95
	global_store_dwordx4 v[124:125], v[128:131], off
	global_store_dwordx4 v[112:113], v[96:99], off offset:256
	v_cvt_pk_bf16_f32 v108, v120, v121
	v_cvt_pk_bf16_f32 v109, v122, v123
	v_lshl_add_u64 v[96:97], v[112:113], 0, s[2:3]
	v_cvt_pk_bf16_f32 v110, v116, v117
	v_cvt_pk_bf16_f32 v111, v118, v119
	v_cvt_pk_bf16_f32 v80, v80, v81
	v_cvt_pk_bf16_f32 v81, v82, v83
	v_cvt_pk_bf16_f32 v82, v76, v77
	v_cvt_pk_bf16_f32 v83, v78, v79
	global_store_dwordx4 v[112:113], v[108:111], off
	global_store_dwordx4 v[96:97], v[80:83], off offset:256
	v_cvt_pk_bf16_f32 v64, v64, v65
	v_cvt_pk_bf16_f32 v65, v66, v67
	v_lshl_add_u64 v[80:81], v[96:97], 0, s[2:3]
	v_cvt_pk_bf16_f32 v66, v60, v61
	v_lshl_add_u64 v[60:61], v[80:81], 0, s[4:5]
	v_cvt_pk_bf16_f32 v72, v72, v73
	v_cvt_pk_bf16_f32 v73, v74, v75
	v_cvt_pk_bf16_f32 v74, v68, v69
	v_cvt_pk_bf16_f32 v67, v62, v63
	v_cvt_pk_bf16_f32 v92, v104, v105
	v_cvt_pk_bf16_f32 v93, v106, v107
	v_cvt_pk_bf16_f32 v94, v100, v101
	v_cvt_pk_bf16_f32 v95, v102, v103
	v_cvt_pk_bf16_f32 v76, v88, v89
	v_cvt_pk_bf16_f32 v77, v90, v91
	v_cvt_pk_bf16_f32 v78, v84, v85
	v_cvt_pk_bf16_f32 v79, v86, v87
	v_cvt_pk_bf16_f32 v75, v70, v71
	v_cvt_pk_bf16_f32 v48, v48, v49
	v_cvt_pk_bf16_f32 v49, v50, v51
	v_cvt_pk_bf16_f32 v50, v44, v45
	v_cvt_pk_bf16_f32 v51, v46, v47
	global_store_dwordx4 v[96:97], v[92:95], off
	global_store_dwordx4 v[80:81], v[76:79], off
	global_store_dwordx4 v[80:81], v[72:75], off offset:256
	global_store_dwordx4 v[60:61], v[48:51], off offset:256
	v_cvt_pk_bf16_f32 v32, v32, v33
	v_cvt_pk_bf16_f32 v33, v34, v35
	v_lshl_add_u64 v[48:49], v[60:61], 0, s[2:3]
	v_cvt_pk_bf16_f32 v34, v28, v29
	v_cvt_pk_bf16_f32 v35, v30, v31
	global_store_dwordx4 v[60:61], v[64:67], off
	global_store_dwordx4 v[48:49], v[32:35], off offset:256
	v_cvt_pk_bf16_f32 v44, v56, v57
	v_cvt_pk_bf16_f32 v45, v58, v59
	v_lshl_add_u64 v[32:33], v[48:49], 0, s[2:3]
	v_cvt_pk_bf16_f32 v46, v52, v53
	v_cvt_pk_bf16_f32 v47, v54, v55
	v_cvt_pk_bf16_f32 v16, v16, v17
	v_cvt_pk_bf16_f32 v17, v18, v19
	v_cvt_pk_bf16_f32 v18, v12, v13
	v_cvt_pk_bf16_f32 v19, v14, v15
	global_store_dwordx4 v[48:49], v[44:47], off
	global_store_dwordx4 v[32:33], v[16:19], off offset:256
	v_cvt_pk_bf16_f32 v28, v40, v41
	v_cvt_pk_bf16_f32 v29, v42, v43
	v_lshl_add_u64 v[16:17], v[32:33], 0, s[2:3]
	v_cvt_pk_bf16_f32 v30, v36, v37
	v_cvt_pk_bf16_f32 v31, v38, v39
	v_cvt_pk_bf16_f32 v12, v24, v25
	v_cvt_pk_bf16_f32 v13, v26, v27
	v_cvt_pk_bf16_f32 v14, v20, v21
	v_cvt_pk_bf16_f32 v15, v22, v23
	v_cvt_pk_bf16_f32 v8, v8, v9
	v_cvt_pk_bf16_f32 v9, v10, v11
	v_cvt_pk_bf16_f32 v10, v4, v5
	v_cvt_pk_bf16_f32 v11, v6, v7
	s_and_b64 vcc, exec, s[6:7]
	s_mov_b64 s[2:3], s[14:15]
	s_mov_b64 s[16:17], s[12:13]
	s_mov_b64 s[8:9], s[10:11]
	s_mov_b32 s4, s56
	s_mov_b32 s5, s28
	global_store_dwordx4 v[32:33], v[28:31], off
	global_store_dwordx4 v[16:17], v[12:15], off
	global_store_dwordx4 v[16:17], v[8:11], off offset:256
	s_cbranch_vccz .LBB0_726
	s_waitcnt vmcnt(0)
	s_movk_i32 s66, 0x100
	v_cmp_gt_u32_e32 vcc, s66, v135
	s_and_saveexec_b64 s[0:1], vcc
	s_cbranch_execz .LBB0_733
	s_barrier
